# shared hand-written weight converter with 3-deep tile prefetch and double-buffered LDS replaces inlined convert loops
# speedup vs baseline: 1.0076x; 1.0076x over previous
; #define LAS __attribute__((address_space(3)))
; __global__ void __launch_bounds__(NTHR, 2) mega_fwd(Params p) {
;     ...
;     bf16_t* W13 = (bf16_t*)(ws + WS_W13); bf16_t* W2 = (bf16_t*)(ws + WS_W2); bf16_t* WA = (bf16_t*)(ws + WS_WA); bf16_t* WB = (bf16_t*)(ws + WS_WB);
;     bf16_t* POOLW = (bf16_t*)(ws + WS_POOLW); float* ROPE = (float*)(ws + WS_ROPE); bf16_t* XN = (bf16_t*)(ws + WS_XN); bf16_t* BIG = (bf16_t*)(ws + WS_BIG);
;     bf16_t* OG = (bf16_t*)(ws + WS_OG); bf16_t* POOLED = (bf16_t*)(ws + WS_OG); float* LSE = (float*)(ws + WS_LSE);
;     float* H = p.out;
;     const int lo = p.ph_lo, hi = p.ph_hi;
;     volatile LAS unsigned* bst = (volatile LAS unsigned*)(lds + ATT_LDS);
;     if (threadIdx.x < 4) bst[threadIdx.x] = 0u;
;     __syncthreads();
;     XcdBarrier xbar; xbar.bar = (unsigned*)(ws + WS_BAR); xbar.x = 0; xbar.st = bst;
;     if (hi - lo > 1) xbar = xcd_barrier_post((unsigned*)(ws + WS_BAR), bst);
;     if (lo < 0) cg::this_grid().sync();
;     ...
;     const size_t WSZ = (size_t)DM * DFF;
;     bf16_t* HB = (bf16_t*)(ws + WS_HB); float* RS = (float*)(ws + WS_RS);
;     const float* NG = p.norm_g;
;     if (IN(0)) {
;         convert_w((LAS float*)lds, p.w2, DFF, DM, W2, 0, 0, nullptr, G, bid);
;         convert_w((LAS float*)lds, p.w1, DM, DFF, W13, 1, 0, NG, G, bid);
;         convert_w((LAS float*)lds, p.w3, DM, DFF, W13, 1, 1, NG, G, bid);
.LBB0_19:
	v_readlane_b32 s0, v252, 0
	s_add_u32 s38, s82, 0x5800000
	v_readlane_b32 s1, v252, 1
	s_addc_u32 s39, s83, 0
	s_load_dwordx2 s[0:1], s[0:1], 0x10
	s_add_u32 s36, s82, 0xa480000
	s_addc_u32 s37, s83, 0
	s_add_u32 s2, s82, 0x2a980000
	s_addc_u32 s3, s83, 0
	s_waitcnt lgkmcnt(0)
	v_writelane_b32 v252, s0, 7
	s_cmp_lt_i32 s84, 1
	s_nop 0
	v_writelane_b32 v252, s1, 8
	s_cselect_b64 s[0:1], -1, 0
	s_cmp_gt_i32 s85, 0
	s_cselect_b64 s[4:5], -1, 0
	s_and_b64 s[4:5], s[0:1], s[4:5]
	s_andn2_b64 vcc, exec, s[4:5]
	s_cbranch_vccnz .LBB0_61
	s_mov_b32 s98, 0
	s_branch .Lcv_entry
.Lcv_ret_0:
	s_mov_b32 s98, 1
	s_branch .Lcv_entry
.Lcv_ret_1:
	s_mov_b32 s98, 2
	s_branch .Lcv_entry
.Lcv_ret_2:
	s_cmpk_lt_i32 s79, 0
	s_cselect_b64 s[0:1], -1, 0
	s_cmpk_gt_i32 s79, -1
	s_mov_b64 s[6:7], -1
	s_cbranch_scc0 .LBB0_22
	s_mov_b64 s[6:7], 0

; #define LAS __attribute__((address_space(3)))
; __device__ __forceinline__ void convert_w(LAS float* tile, const float* __restrict__ src, int K, int N, bf16_t* __restrict__ dst, int mode, int sidx, const float* __restrict__ gk, int G, int bid) {
;     ...
;     if (bid < ntile) {
;         const int k0 = (bid % tk) * 64, n0 = (bid / tk) * 64;
; #pragma unroll
;         for (int i = 0; i < 2; ++i) pv[i] = __builtin_nontemporal_load((const f32x4*)(src + (size_t)(k0 + kk + 32 * i) * N + n0 + n4));
; __global__ void __launch_bounds__(NTHR, 2) mega_fwd(Params p) {
;     ...
;     if (IN(2)) { Gemm g{BIG, W2, DFF, DFF, SEQ, DM, DFF, 0, 1}; StaticOrder S; S.init(SEQ, DM, G, bid, 4); EpiResid<true, 1> E{RS}; gemm_phase(lds, g, S, E); }
;     if (IN(2)) convert_w((LAS float*)lds, p.w_in, DM, 4096, WA, 0, 0, NG + 1 * DM, G, bid);
.LBB0_233:
	s_mov_b32 s98, 3
	s_branch .Lcv_entry
.Lcv_ret_3:
	s_cmpk_gt_i32 s79, -1
	s_cbranch_scc1 .LBB0_238
	v_readlane_b32 s0, v252, 0
	s_ashr_i32 s2, s79, 31
	v_readlane_b32 s1, v252, 1
	s_lshr_b32 s2, s2, 27
	s_load_dwordx2 s[0:1], s[0:1], 0x30
	s_add_i32 s2, s79, s2
	s_and_b32 s3, s2, 0x3ffffe0
	s_lshl_b32 s2, s2, 1
	s_sub_i32 s3, s79, s3
	s_andn2_b32 s2, s2, 63
	v_lshl_or_b32 v0, s3, 6, v161
	s_ashr_i32 s3, s2, 31
	s_lshl_b64 s[2:3], s[2:3], 2
	s_waitcnt lgkmcnt(0)
	v_and_b32_e32 v1, 60, v162
	s_add_u32 s2, s0, s2
	s_addc_u32 s3, s1, s3
	v_lshlrev_b32_e32 v8, 2, v1
	v_mov_b32_e32 v9, 0
	v_ashrrev_i32_e32 v1, 31, v0
	v_lshl_add_u64 v[2:3], s[2:3], 0, v[8:9]
	v_lshlrev_b64 v[0:1], 14, v[0:1]
	v_lshl_add_u64 v[10:11], v[2:3], 0, v[0:1]
	s_mov_b32 s2, 0x80000
	v_add_co_u32_e32 v12, vcc, s2, v10
	v_add_u32_e32 v15, 0, v8
	s_nop 0
	v_addc_co_u32_e32 v13, vcc, 0, v11, vcc
	global_load_dwordx4 v[0:3], v[10:11], off nt
	global_load_dwordx4 v[4:7], v[12:13], off nt
	v_lshl_add_u64 v[10:11], s[0:1], 0, v[8:9]
	v_lshlrev_b32_e32 v8, 3, v224
	v_and_b32_e32 v20, 56, v8
	v_readlane_b32 s0, v252, 7
	v_lshlrev_b32_e32 v8, 2, v20
	v_readlane_b32 s1, v252, 8
	v_lshl_add_u32 v18, v160, 2, 0
	v_mul_u32_u24_e32 v19, 0x104, v20
	v_lshl_add_u64 v[12:13], s[0:1], 0, v[8:9]
	v_mul_u32_u24_e32 v8, 0x104, v161
	s_mov_b64 s[0:1], 0x2000
	s_lshl_b32 s3, s78, 6
	v_add_u32_e32 v15, v15, v8
	v_lshl_add_u64 v[12:13], v[12:13], 0, s[0:1]
	s_lshl_b32 s2, s79, 6
	v_or_b32_e32 v14, s3, v161
	v_add_u32_e32 v16, 0x2080, v15
	v_add_u32_e32 v17, 0x2088, v15
	v_add_u32_e32 v18, v18, v19
	v_lshlrev_b32_e32 v8, 1, v20
	s_mov_b32 s5, s79
	s_branch .LBB0_236

; #define LAS __attribute__((address_space(3)))
; __device__ __forceinline__ void convert_w(LAS float* tile, const float* __restrict__ src, int K, int N, bf16_t* __restrict__ dst, int mode, int sidx, const float* __restrict__ gk, int G, int bid) {
;     ...
;     if (bid < ntile) {
;         const int k0 = (bid % tk) * 64, n0 = (bid / tk) * 64;
; __global__ void __launch_bounds__(NTHR, 2) mega_fwd(Params p) {
;     ...
;     if (IN(4)) convpool_phase(BIG, p.conv_w, XN, POOLED, G, bid);
;     if (IN(4)) {
;         convert_w((LAS float*)lds, p.w_out, DM, DM, WB, 0, 0, nullptr, G, bid);
.LBB0_378:
	s_or_b64 exec, exec, s[46:47]
	s_mov_b32 s98, 4
	s_branch .Lcv_entry
.Lcv_ret_4:
	v_lshlrev_b32_e32 v0, 2, v224
	v_lshrrev_b32_e32 v21, 4, v224
	s_cmpk_lt_i32 s79, 0
	v_and_b32_e32 v14, 60, v0
	s_cbranch_scc1 .LBB0_380
	v_lshlrev_b32_e32 v0, 3, v224
	v_mov_b32_e32 v15, 0
	v_and_b32_e32 v8, 56, v0
	v_lshrrev_b32_e32 v18, 3, v224
	v_mov_b32_e32 v9, v15
	v_mul_u32_u24_e32 v16, 0x104, v21
	v_mul_u32_u24_e32 v17, 0x104, v8
	s_cbranch_execz .LBB0_381
	s_branch .LBB0_385

; #define LAS __attribute__((address_space(3)))
; #define PG8_WAIT_V(n) asm volatile("s_waitcnt vmcnt(" #n ")" ::: "memory")
; #define PG8_BAR __builtin_amdgcn_s_barrier()
; template <class Epi>
; __device__ __forceinline__ void gemm_phase(LAS unsigned char* lds, const Gemm g, const StaticOrder S, const Epi E) {
;     ...
;     PG8_WAIT_V(0);
;     PG8_BAR;
; __global__ void __launch_bounds__(NTHR, 2) mega_fwd(Params p) {
;     ...
;     if (IN(6)) {
;         convert_w((LAS float*)lds, p.w2 + (size_t)1 * WSZ, DFF, DM, W2 + (size_t)DM * DFF, 0, 0, nullptr, G, bid);
;         convert_w((LAS float*)lds, p.w1 + (size_t)1 * WSZ, DM, DFF, W13 + (size_t)2 * DFF * DM, 1, 0, NG + 2 * DM, G, bid);
;         convert_w((LAS float*)lds, p.w3 + (size_t)1 * WSZ, DM, DFF, W13 + (size_t)2 * DFF * DM, 1, 1, NG + 2 * DM, G, bid);
.LBB0_592:
	s_waitcnt vmcnt(0)
	v_readlane_b32 s56, v252, 15
	v_readlane_b32 s57, v252, 16
	s_barrier
	s_mov_b32 s98, 5
	s_branch .Lcv_entry
.Lcv_ret_5:
	s_mov_b32 s98, 6
	s_branch .Lcv_entry
.Lcv_ret_6:
	s_mov_b32 s98, 7
	s_branch .Lcv_entry
.Lcv_ret_7:
	s_cmpk_gt_i32 s79, -1
	s_mov_b64 s[0:1], -1
	s_cbranch_scc0 .LBB0_553

; __device__ __forceinline__ void convert_w(LAS float* tile, const float* __restrict__ src, int K, int N, bf16_t* __restrict__ dst, int mode, int sidx, const float* __restrict__ gk, int G, int bid) {
;     const int tid = threadIdx.x;
;     const int tk = K / 64, tn = N / 64, ntile = tk * tn;
;     const int kk = tid >> 4, n4 = (tid & 15) * 4;
; __global__ void __launch_bounds__(NTHR, 2) mega_fwd(Params p) {
;     ...
;         convert_w((LAS float*)lds, p.w2, DFF, DM, W2, 0, 0, nullptr, G, bid);
;         convert_w((LAS float*)lds, p.w1, DM, DFF, W13, 1, 0, NG, G, bid);
;         convert_w((LAS float*)lds, p.w3, DM, DFF, W13, 1, 1, NG, G, bid);
;         rope_phase(p.pos, p.inv, ROPE, G, bid);
;         cast_phase(p.x, HB, RS, G, bid);
;     }
;     SEAM(0);
;     if (IN(1)) { Gemm g{HB, W13, DM, DM, SEQ, 2 * DFF, DM, 0}; StaticOrder S; S.init(SEQ, 2 * DFF, G, bid); EpiSwiglu E{BIG, DFF, RS + 0 * SEQ}; gemm_phase(lds, g, S, E); }
;     SEAM(1);
;     if (IN(2)) { Gemm g{BIG, W2, DFF, DFF, SEQ, DM, DFF, 0, 1}; StaticOrder S; S.init(SEQ, DM, G, bid, 4); EpiResid<true, 1> E{RS}; gemm_phase(lds, g, S, E); }
;     if (IN(2)) convert_w((LAS float*)lds, p.w_in, DM, 4096, WA, 0, 0, NG + 1 * DM, G, bid);
;     SEAM(2);
;     if (IN(3)) { Gemm g{HB, WA, DM, DM, SEQ, 4096, DM, 0}; StaticOrder S; S.init(SEQ, 4096, G, bid); EpiBf16 E{BIG, 4096, nullptr, RS + 1 * SEQ}; gemm_phase(lds, g, S, E); }
;     SEAM(3);
;     if (IN(4)) convpool_phase(BIG, p.conv_w, XN, POOLED, G, bid);
;     if (IN(4)) {
;         convert_w((LAS float*)lds, p.w_out, DM, DM, WB, 0, 0, nullptr, G, bid);
;         for (int gq = 0; gq < 4; ++gq) convert_w((LAS float*)lds, p.pool_w + (size_t)gq * 65536, 256, 256, POOLW + (size_t)gq * 65536, 0, 0, nullptr, G, bid);
;     }
;     SEAM(4);
;     if (IN(5)) { Gemm g{POOLED, POOLW, 1024, 256, SEQ, 1024, 256, 512}; StaticOrder S; S.init(SEQ, 1024, G, bid); EpiBf16 E{XN + 1024, DM, p.pool_scale, nullptr}; gemm_phase(lds, g, S, E); }
;     SEAM(5);
;     if (IN(6)) { Gemm g{XN, WB, DM, DM, SEQ, DM, DM, 0}; StaticOrder S; S.init(SEQ, DM, G, bid, 4); EpiResid<false, 2> E{RS}; gemm_phase(lds, g, S, E); }
;     if (IN(6)) {
;         convert_w((LAS float*)lds, p.w2 + (size_t)1 * WSZ, DFF, DM, W2 + (size_t)DM * DFF, 0, 0, nullptr, G, bid);
;         convert_w((LAS float*)lds, p.w1 + (size_t)1 * WSZ, DM, DFF, W13 + (size_t)2 * DFF * DM, 1, 0, NG + 2 * DM, G, bid);
.LBB0_726:
	s_or_b64 exec, exec, s[2:3]
	s_waitcnt lgkmcnt(0)
	s_barrier
	s_branch .LBB0_727
.Lcv_entry:
	v_writelane_b32 v253, s0, 0
	v_writelane_b32 v253, s1, 1
	v_writelane_b32 v253, s2, 2
	v_writelane_b32 v253, s3, 3
	v_writelane_b32 v253, s4, 4
	v_writelane_b32 v253, s5, 5
	v_writelane_b32 v253, s6, 6
	v_writelane_b32 v253, s7, 7
	v_writelane_b32 v253, s8, 8
	v_writelane_b32 v253, s9, 9
	v_writelane_b32 v253, s10, 10
	v_writelane_b32 v253, s11, 11
	v_writelane_b32 v253, s12, 12
	v_writelane_b32 v253, s13, 13
	v_writelane_b32 v253, s14, 14
	v_writelane_b32 v253, s15, 15
	v_writelane_b32 v253, s16, 16
	v_writelane_b32 v253, s17, 17
	v_writelane_b32 v253, s18, 18
	v_writelane_b32 v253, s19, 19
	v_writelane_b32 v253, s20, 20
	v_writelane_b32 v253, s21, 21
	v_writelane_b32 v253, s22, 22
	v_writelane_b32 v253, s23, 23
	v_writelane_b32 v253, s24, 24
	v_writelane_b32 v253, s25, 25
	v_writelane_b32 v253, s26, 26
	v_writelane_b32 v253, s27, 27
	v_writelane_b32 v253, s28, 28
	v_writelane_b32 v253, s29, 29
	v_writelane_b32 v253, s30, 30
	v_writelane_b32 v253, s31, 31
	v_readlane_b32 s0, v252, 0
	v_readlane_b32 s1, v252, 1
	s_cmp_eq_u32 s98, 0
	s_cbranch_scc1 .Lcv_par_0
	s_cmp_eq_u32 s98, 1
	s_cbranch_scc1 .Lcv_par_1
	s_cmp_eq_u32 s98, 2
	s_cbranch_scc1 .Lcv_par_2
	s_cmp_eq_u32 s98, 3
	s_cbranch_scc1 .Lcv_par_3
	s_cmp_eq_u32 s98, 4
	s_cbranch_scc1 .Lcv_par_4
	s_cmp_eq_u32 s98, 5
	s_cbranch_scc1 .Lcv_par_5
	s_cmp_eq_u32 s98, 6
	s_cbranch_scc1 .Lcv_par_6
	s_cmp_eq_u32 s98, 7
	s_cbranch_scc1 .Lcv_par_7
	s_cmp_eq_u32 s98, 8
	s_cbranch_scc1 .Lcv_par_8
	s_cmp_eq_u32 s98, 9
	s_cbranch_scc1 .Lcv_par_9
	s_cmp_eq_u32 s98, 10
	s_cbranch_scc1 .Lcv_par_10
	s_cmp_eq_u32 s98, 11
	s_cbranch_scc1 .Lcv_par_11
	s_cmp_eq_u32 s98, 12
	s_cbranch_scc1 .Lcv_par_12
	s_cmp_eq_u32 s98, 13
	s_cbranch_scc1 .Lcv_par_13
	s_cmp_eq_u32 s98, 14
	s_cbranch_scc1 .Lcv_par_14
	s_cmp_eq_u32 s98, 15
	s_cbranch_scc1 .Lcv_par_15
	s_branch .Lcv_par_0
.Lcv_par_0:
	s_load_dwordx2 s[2:3], s[0:1], 0x28
	s_mov_b32 s22, 0x0
	s_mov_b32 s23, 0x5800000
	s_movk_i32 s6, 0x800
	s_movk_i32 s7, 0x1600
	s_movk_i32 s8, 0xb00
	s_mov_b32 s9, 0
	s_movk_i32 s10, 0x0
	s_mov_b32 s11, 0
	s_mov_b32 s24, 0x0
	s_mov_b32 s25, 88
	s_movk_i32 s26, 0x0
	s_branch .Lcv_common
.Lcv_par_1:
	s_load_dwordx2 s[2:3], s[0:1], 0x18
	s_load_dwordx2 s[12:13], s[0:1], 0x10
	s_mov_b32 s22, 0x0
	s_mov_b32 s23, 0x0
	s_movk_i32 s6, 0x1600
	s_movk_i32 s7, 0x800
	s_movk_i32 s8, 0xb00
	s_mov_b32 s9, 1
	s_movk_i32 s10, 0x0
	s_mov_b32 s11, 1
	s_mov_b32 s24, 0x0
	s_mov_b32 s25, 32
	s_movk_i32 s26, 0x0
	s_branch .Lcv_common
.Lcv_par_2:
	s_load_dwordx2 s[2:3], s[0:1], 0x20
	s_load_dwordx2 s[12:13], s[0:1], 0x10
	s_mov_b32 s22, 0x0
	s_mov_b32 s23, 0x0
	s_movk_i32 s6, 0x1600
	s_movk_i32 s7, 0x800
	s_movk_i32 s8, 0xb00
	s_mov_b32 s9, 1
	s_movk_i32 s10, 0x80
	s_mov_b32 s11, 1
	s_mov_b32 s24, 0x0
	s_mov_b32 s25, 32
	s_movk_i32 s26, 0x0
	s_branch .Lcv_common
.Lcv_par_3:
	s_load_dwordx2 s[2:3], s[0:1], 0x30
	s_load_dwordx2 s[12:13], s[0:1], 0x10
	s_mov_b32 s22, 0x0
	s_mov_b32 s23, 0x8400000
	s_movk_i32 s6, 0x1000
	s_movk_i32 s7, 0x800
	s_movk_i32 s8, 0x800
	s_mov_b32 s9, 0
	s_movk_i32 s10, 0x0
	s_mov_b32 s11, 1
	s_mov_b32 s24, 0x2000
	s_mov_b32 s25, 32
	s_movk_i32 s26, 0x0
	s_branch .Lcv_common
.Lcv_par_4:
	s_load_dwordx2 s[2:3], s[0:1], 0x50
	s_mov_b32 s22, 0x0
	s_mov_b32 s23, 0x9c00000
	s_movk_i32 s6, 0x800
	s_movk_i32 s7, 0x800
	s_movk_i32 s8, 0x400
	s_mov_b32 s9, 0
	s_movk_i32 s10, 0x0
	s_mov_b32 s11, 0
	s_mov_b32 s24, 0x0
	s_mov_b32 s25, 32
	s_movk_i32 s26, 0x0
	s_branch .Lcv_common
.Lcv_par_5:
	s_load_dwordx2 s[2:3], s[0:1], 0x28
	s_mov_b32 s22, 0x2c00000
	s_mov_b32 s23, 0x6e00000
	s_movk_i32 s6, 0x800
	s_movk_i32 s7, 0x1600
	s_movk_i32 s8, 0xb00
	s_mov_b32 s9, 0
	s_movk_i32 s10, 0x0
	s_mov_b32 s11, 0
	s_mov_b32 s24, 0x0
	s_mov_b32 s25, 88
	s_movk_i32 s26, 0x0
	s_branch .Lcv_common
.Lcv_par_6:
	s_load_dwordx2 s[2:3], s[0:1], 0x18
	s_load_dwordx2 s[12:13], s[0:1], 0x10
	s_mov_b32 s22, 0x2c00000
	s_mov_b32 s23, 0x2c00000
	s_movk_i32 s6, 0x1600
	s_movk_i32 s7, 0x800
	s_movk_i32 s8, 0xb00
	s_mov_b32 s9, 1
	s_movk_i32 s10, 0x0
	s_mov_b32 s11, 1
	s_mov_b32 s24, 0x4000
	s_mov_b32 s25, 32
	s_movk_i32 s26, 0x0
	s_branch .Lcv_common
.Lcv_par_7:
	s_load_dwordx2 s[2:3], s[0:1], 0x20
	s_load_dwordx2 s[12:13], s[0:1], 0x10
	s_mov_b32 s22, 0x2c00000
	s_mov_b32 s23, 0x2c00000
	s_movk_i32 s6, 0x1600
	s_movk_i32 s7, 0x800
	s_movk_i32 s8, 0xb00
	s_mov_b32 s9, 1
	s_movk_i32 s10, 0x80
	s_mov_b32 s11, 1
	s_mov_b32 s24, 0x4000
	s_mov_b32 s25, 32
	s_movk_i32 s26, 0x0
	s_branch .Lcv_common
.Lcv_par_8:
	s_load_dwordx2 s[2:3], s[0:1], 0x28
	s_mov_b32 s22, 0x5800000
	s_mov_b32 s23, 0x5800000
	s_movk_i32 s6, 0x800
	s_movk_i32 s7, 0x1600
	s_movk_i32 s8, 0xb00
	s_mov_b32 s9, 0
	s_movk_i32 s10, 0x0
	s_mov_b32 s11, 0
	s_mov_b32 s24, 0x0
	s_mov_b32 s25, 88
	s_movk_i32 s26, 0x0
	s_branch .Lcv_common
.Lcv_par_9:
	s_load_dwordx2 s[2:3], s[0:1], 0x18
	s_load_dwordx2 s[12:13], s[0:1], 0x10
	s_mov_b32 s22, 0x5800000
	s_mov_b32 s23, 0x0
	s_movk_i32 s6, 0x1600
	s_movk_i32 s7, 0x800
	s_movk_i32 s8, 0xb00
	s_mov_b32 s9, 1
	s_movk_i32 s10, 0x0
	s_mov_b32 s11, 1
	s_mov_b32 s24, 0x6000
	s_mov_b32 s25, 32
	s_movk_i32 s26, 0x0
	s_branch .Lcv_common
.Lcv_par_10:
	s_load_dwordx2 s[2:3], s[0:1], 0x20
	s_load_dwordx2 s[12:13], s[0:1], 0x10
	s_mov_b32 s22, 0x5800000
	s_mov_b32 s23, 0x0
	s_movk_i32 s6, 0x1600
	s_movk_i32 s7, 0x800
	s_movk_i32 s8, 0xb00
	s_mov_b32 s9, 1
	s_movk_i32 s10, 0x80
	s_mov_b32 s11, 1
	s_mov_b32 s24, 0x6000
	s_mov_b32 s25, 32
	s_movk_i32 s26, 0x0
	s_branch .Lcv_common
; #define LAS __attribute__((address_space(3)))
; #define SEAM(k) do { if (IN(k) && IN((k) + 1)) xcd_barrier(xbar); } while (0)
; __device__ __forceinline__ void convert_w(LAS float* tile, const float* __restrict__ src, int K, int N, bf16_t* __restrict__ dst, int mode, int sidx, const float* __restrict__ gk, int G, int bid) {
;     const int tid = threadIdx.x;
;     const int tk = K / 64, tn = N / 64, ntile = tk * tn;
;     const int kk = tid >> 4, n4 = (tid & 15) * 4;
;     f32x4 pv[2];
;     if (bid < ntile) {
;         const int k0 = (bid % tk) * 64, n0 = (bid / tk) * 64;
; #pragma unroll
;         for (int i = 0; i < 2; ++i) pv[i] = __builtin_nontemporal_load((const f32x4*)(src + (size_t)(k0 + kk + 32 * i) * N + n0 + n4));
;     }
; __global__ void __launch_bounds__(NTHR, 2) mega_fwd(Params p) {
;     ...
;     if (IN(11)) convert_w((LAS float*)lds, p.w_qkv, DM, 6144, WA, 2, 0, NG + 4 * DM, G, bid);
;     SEAM(11);
;     if (IN(12)) { Gemm g{HB, WA, DM, DM, SEQ, 6144, DM, 0}; StaticOrder S; S.init(SEQ, 6144, G, bid); EpiQkv E{BIG, 6144, ROPE, RS + 4 * SEQ}; gemm_phase(lds, g, S, E); }
;     SEAM(12);
;     if (IN(13)) attn_phase(lds, BIG, OG, LSE, G, bid);
;     SEAM(13);
;     if (IN(14)) combine_phase(OG, LSE, XN, G, bid);
;     if (IN(14)) convert_w((LAS float*)lds, p.w_o, DM, DM, WB, 0, 0, nullptr, G, bid);
;     SEAM(14);
;     if (IN(15)) { Gemm g{XN, WB, DM, DM, SEQ, DM, DM, 0}; StaticOrder S; S.init(SEQ, DM, G, bid, 4); EpiResid<false, 5> E{RS}; gemm_phase(lds, g, S, E); }
;     if (IN(15)) {
;         convert_w((LAS float*)lds, p.w2 + (size_t)3 * WSZ, DFF, DM, W2 + (size_t)DM * DFF, 0, 0, nullptr, G, bid);
;         convert_w((LAS float*)lds, p.w1 + (size_t)3 * WSZ, DM, DFF, W13 + (size_t)2 * DFF * DM, 1, 0, NG + 5 * DM, G, bid);
;         convert_w((LAS float*)lds, p.w3 + (size_t)3 * WSZ, DM, DFF, W13 + (size_t)2 * DFF * DM, 1, 1, NG + 5 * DM, G, bid);
.Lcv_par_11:
	s_load_dwordx2 s[2:3], s[0:1], 0x58
	s_load_dwordx2 s[12:13], s[0:1], 0x10
	s_mov_b32 s22, 0x0
	s_mov_b32 s23, 0x8400000
	s_movk_i32 s6, 0x1800
	s_movk_i32 s7, 0x800
	s_movk_i32 s8, 0xc00
	s_mov_b32 s9, 2
	s_movk_i32 s10, 0x0
	s_mov_b32 s11, 1
	s_mov_b32 s24, 0x8000
	s_mov_b32 s25, 32
	s_movk_i32 s26, 0x1000
	s_branch .Lcv_common
.Lcv_par_12:
	s_load_dwordx2 s[2:3], s[0:1], 0x60
	s_mov_b32 s22, 0x0
	s_mov_b32 s23, 0x9c00000
	s_movk_i32 s6, 0x800
	s_movk_i32 s7, 0x800
	s_movk_i32 s8, 0x400
	s_mov_b32 s9, 0
	s_movk_i32 s10, 0x0
	s_mov_b32 s11, 0
	s_mov_b32 s24, 0x0
	s_mov_b32 s25, 32
	s_movk_i32 s26, 0x0
	s_branch .Lcv_common
.Lcv_par_13:
	s_load_dwordx2 s[2:3], s[0:1], 0x28
	s_mov_b32 s22, 0x8400000
	s_mov_b32 s23, 0x6e00000
	s_movk_i32 s6, 0x800
	s_movk_i32 s7, 0x1600
	s_movk_i32 s8, 0xb00
	s_mov_b32 s9, 0
	s_movk_i32 s10, 0x0
	s_mov_b32 s11, 0
	s_mov_b32 s24, 0x0
	s_mov_b32 s25, 88
	s_movk_i32 s26, 0x0
	s_branch .Lcv_common
.Lcv_par_14:
	s_load_dwordx2 s[2:3], s[0:1], 0x18
	s_load_dwordx2 s[12:13], s[0:1], 0x10
	s_mov_b32 s22, 0x8400000
	s_mov_b32 s23, 0x2c00000
	s_movk_i32 s6, 0x1600
	s_movk_i32 s7, 0x800
	s_movk_i32 s8, 0xb00
	s_mov_b32 s9, 1
	s_movk_i32 s10, 0x0
	s_mov_b32 s11, 1
	s_mov_b32 s24, 0xa000
	s_mov_b32 s25, 32
	s_movk_i32 s26, 0x0
	s_branch .Lcv_common
.Lcv_par_15:
	s_load_dwordx2 s[2:3], s[0:1], 0x20
	s_load_dwordx2 s[12:13], s[0:1], 0x10
	s_mov_b32 s22, 0x8400000
	s_mov_b32 s23, 0x2c00000
	s_movk_i32 s6, 0x1600
	s_movk_i32 s7, 0x800
	s_movk_i32 s8, 0xb00
	s_mov_b32 s9, 1
	s_movk_i32 s10, 0x80
	s_mov_b32 s11, 1
	s_mov_b32 s24, 0xa000
	s_mov_b32 s25, 32
	s_movk_i32 s26, 0x0
	s_branch .Lcv_common
.Lcv_common:
	s_waitcnt lgkmcnt(0)
	s_add_u32 s2, s2, s22
	s_addc_u32 s3, s3, 0
	s_add_u32 s4, s82, s23
	s_addc_u32 s5, s83, 0
	s_add_u32 s12, s12, s24
	s_addc_u32 s13, s13, 0
	s_mov_b32 s27, s26
	s_mov_b32 s16, s78
	s_lshl_b32 s17, s78, 1
	s_mov_b32 s14, s79
	v_lshrrev_b32_e32 v0, 4, v224
	v_and_b32_e32 v1, 15, v224
	v_lshlrev_b32_e32 v1, 2, v1
	v_mul_lo_u32 v2, v0, s6
	v_add_lshl_u32 v2, v2, v1, 2
	s_lshl_b32 s22, s6, 7
	v_add_u32_e32 v3, s22, v2
	v_mul_u32_u24_e32 v4, 0x41, v0
	v_add_lshl_u32 v4, v4, v1, 2
	v_add_u32_e32 v5, 0x2080, v4
	v_add_u32_e32 v6, 0x2088, v4
	v_lshrrev_b32_e32 v7, 3, v224
	v_and_b32_e32 v8, 7, v224
	v_lshlrev_b32_e32 v8, 3, v8
	v_mul_u32_u24_e32 v9, 0x41, v8
	v_add_lshl_u32 v9, v9, v7, 2
	v_add_u32_e32 v10, 0x400, v9
	v_mul_lo_u32 v11, v7, s7
	v_add_lshl_u32 v11, v11, v8, 1
	v_bfe_u32 v12, v7, 2, 2
	v_lshlrev_b32_e32 v12, 3, v12
	v_bfe_u32 v13, v7, 4, 1
	v_lshl_or_b32 v12, v13, 2, v12
	v_and_b32_e32 v13, 3, v7
	v_or_b32_e32 v12, v12, v13
	v_cmp_gt_u32_e32 vcc, 32, v7
	s_nop 1
	v_cndmask_b32_e32 v12, v7, v12, vcc
	v_mul_lo_u32 v12, v12, s7
	v_add_lshl_u32 v12, v12, v8, 1
	v_lshlrev_b32_e32 v14, 2, v8
	v_add_u32_e32 v14, 0x10000, v14
	v_lshlrev_b32_e32 v13, 4, v224
	v_add_u32_e32 v13, 0x10000, v13
	s_cmp_eq_u32 s11, 0
	s_cbranch_scc1 .Lcv_nogk0
	v_lshlrev_b32_e32 v15, 4, v224
	global_load_dwordx4 v[48:51], v15, s[12:13]
.Lcv_nogk0:
	s_mov_b32 s15, s14
	s_cmp_ge_u32 s15, s8
	s_cbranch_scc1 .Lcv_pro_done
	s_lshr_b32 s28, s15, 5
	s_mul_hi_u32 s29, s15, 0x2e8ba2e9
	s_lshr_b32 s29, s29, 4
	s_cmpk_eq_u32 s7, 0x1600
	s_cselect_b32 s28, s29, s28
	s_mul_i32 s29, s28, s25
	s_sub_u32 s29, s15, s29
	s_lshl_b32 s30, s6, 8
	s_mul_i32 s30, s29, s30
	s_lshl_b32 s31, s28, 8
	s_add_u32 s30, s30, s31
	s_add_u32 s18, s2, s30
	s_addc_u32 s19, s3, 0
	global_load_dwordx4 v[16:19], v2, s[18:19] nt
	global_load_dwordx4 v[20:23], v3, s[18:19] nt
	s_add_u32 s15, s15, s16
	s_cmp_ge_u32 s15, s8
	s_cbranch_scc1 .Lcv_pro_done
	s_lshr_b32 s28, s15, 5
	s_mul_hi_u32 s29, s15, 0x2e8ba2e9
	s_lshr_b32 s29, s29, 4
	s_cmpk_eq_u32 s7, 0x1600
	s_cselect_b32 s28, s29, s28
	s_mul_i32 s29, s28, s25
	s_sub_u32 s29, s15, s29
	s_lshl_b32 s30, s6, 8
	s_mul_i32 s30, s29, s30
	s_lshl_b32 s31, s28, 8
	s_add_u32 s30, s30, s31
	s_add_u32 s18, s2, s30
	s_addc_u32 s19, s3, 0
	global_load_dwordx4 v[24:27], v2, s[18:19] nt
	global_load_dwordx4 v[28:31], v3, s[18:19] nt
	s_add_u32 s15, s15, s16
	s_cmp_ge_u32 s15, s8
	s_cbranch_scc1 .Lcv_pro_done
	s_lshr_b32 s28, s15, 5
	s_mul_hi_u32 s29, s15, 0x2e8ba2e9
	s_lshr_b32 s29, s29, 4
	s_cmpk_eq_u32 s7, 0x1600
	s_cselect_b32 s28, s29, s28
	s_mul_i32 s29, s28, s25
	s_sub_u32 s29, s15, s29
	s_lshl_b32 s30, s6, 8
	s_mul_i32 s30, s29, s30
	s_lshl_b32 s31, s28, 8
	s_add_u32 s30, s30, s31
	s_add_u32 s18, s2, s30
	s_addc_u32 s19, s3, 0
	global_load_dwordx4 v[32:35], v2, s[18:19] nt
	global_load_dwordx4 v[36:39], v3, s[18:19] nt
	s_add_u32 s15, s15, s16
; __device__ __forceinline__ unsigned cvt_pk_bf16(float lo, float hi) { unsigned r; asm volatile("v_cvt_pk_bf16_f32 %0, %1, %2" : "=v"(r) : "v"(lo), "v"(hi)); return r; }
; __device__ __forceinline__ void convert_w(LAS float* tile, const float* __restrict__ src, int K, int N, bf16_t* __restrict__ dst, int mode, int sidx, const float* __restrict__ gk, int G, int bid) {
;     ...
;     for (int t = bid; t < ntile; t += G) {
;         const int k0 = (t % tk) * 64, n0 = (t / tk) * 64;
; #pragma unroll
;         for (int i = 0; i < 2; ++i) {
;             const int k = kk + 32 * i;
;             tile[k * 65 + n4 + 0] = pv[i][0]; tile[k * 65 + n4 + 1] = pv[i][1]; tile[k * 65 + n4 + 2] = pv[i][2]; tile[k * 65 + n4 + 3] = pv[i][3];
;         }
;         __syncthreads();
;         if (t + G < ntile) {
;             const int k1 = ((t + G) % tk) * 64, n1 = ((t + G) / tk) * 64;
; #pragma unroll
;             for (int i = 0; i < 2; ++i) pv[i] = __builtin_nontemporal_load((const f32x4*)(src + (size_t)(k1 + kk + 32 * i) * N + n1 + n4));
;         }
;         const int n = tid >> 3, k8 = (tid & 7) * 8;
;         float f[8];
; #pragma unroll
;         for (int j = 0; j < 8; ++j) f[j] = tile[(k8 + j) * 65 + n];
;         if (gk) {
;             const f32x4 ga = *(const f32x4*)(gk + k0 + k8), gb = *(const f32x4*)(gk + k0 + k8 + 4);
;             f[0] *= ga[0]; f[1] *= ga[1]; f[2] *= ga[2]; f[3] *= ga[3]; f[4] *= gb[0]; f[5] *= gb[1]; f[6] *= gb[2]; f[7] *= gb[3];
;         }
;         u32x4 w; w.x = cvt_pk_bf16(f[0], f[1]); w.y = cvt_pk_bf16(f[2], f[3]); w.z = cvt_pk_bf16(f[4], f[5]); w.w = cvt_pk_bf16(f[6], f[7]);
;         const int nn = n0 + n;
;         int row = nn;
;         if (mode == 1) row = 256 * (nn >> 7) + 128 * sidx + (nn & 127);
;         if (mode == 2 && nn < 4096 && (nn & 127) < 32) { const int d = nn & 31; row = (nn & ~31) + 8 * ((d >> 2) & 3) + 4 * (d >> 4) + (d & 3); }
;         *(u32x4*)(dst + (size_t)row * K + k0 + k8) = w;
;         __syncthreads();
.Lcv_pro_done:
	s_cmp_eq_u32 s11, 0
	s_cbranch_scc1 .Lcv_nogk1
	s_add_u32 s22, s14, s17
	s_cmp_lt_u32 s22, s8
	s_cbranch_scc1 .Lcv_gkfast
	s_waitcnt vmcnt(0)
	s_branch .Lcv_gkw
.Lcv_gkfast:
	s_waitcnt vmcnt(6)
.Lcv_gkw:
	ds_write_b128 v13, v[48:51]
.Lcv_nogk1:
.Lcv_st_p0:
	s_cmp_ge_u32 s14, s8
	s_cbranch_scc1 .Lcv_done
	s_add_u32 s22, s14, s17
	s_cmp_lt_u32 s22, s8
	s_cbranch_scc1 .Lcv_fast_p0
	s_waitcnt vmcnt(0)
	s_branch .Lcv_go_p0
.Lcv_fast_p0:
	s_waitcnt vmcnt(4)
.Lcv_go_p0:
	ds_write2_b32 v4, v16, v17 offset1:1
	ds_write2_b32 v4, v18, v19 offset0:2 offset1:3
	ds_write2_b32 v5, v20, v21 offset1:1
	ds_write2_b32 v6, v22, v23 offset1:1
	s_waitcnt lgkmcnt(0)
	s_barrier
	s_add_u32 s23, s22, s16
	s_cmp_ge_u32 s23, s8
	s_cbranch_scc1 .Lcv_nold_p0
	s_lshr_b32 s28, s23, 5
	s_mul_hi_u32 s29, s23, 0x2e8ba2e9
	s_lshr_b32 s29, s29, 4
	s_cmpk_eq_u32 s7, 0x1600
	s_cselect_b32 s28, s29, s28
	s_mul_i32 s29, s28, s25
	s_sub_u32 s29, s23, s29
	s_lshl_b32 s30, s6, 8
	s_mul_i32 s30, s29, s30
	s_lshl_b32 s31, s28, 8
	s_add_u32 s30, s30, s31
	s_add_u32 s18, s2, s30
	s_addc_u32 s19, s3, 0
	global_load_dwordx4 v[16:19], v2, s[18:19] nt
	global_load_dwordx4 v[20:23], v3, s[18:19] nt
.Lcv_nold_p0:
	ds_read2_b32 v[40:41], v9 offset1:65
	ds_read2_b32 v[42:43], v9 offset0:130 offset1:195
	ds_read2_b32 v[44:45], v10 offset0:4 offset1:69
	ds_read2_b32 v[46:47], v10 offset0:134 offset1:199
	s_lshr_b32 s28, s14, 5
	s_mul_hi_u32 s29, s14, 0x2e8ba2e9
	s_lshr_b32 s29, s29, 4
	s_cmpk_eq_u32 s7, 0x1600
	s_cselect_b32 s28, s29, s28
	s_mul_i32 s29, s28, s25
	s_sub_u32 s29, s14, s29
	s_cmp_eq_u32 s11, 0
	s_cbranch_scc1 .Lcv_nogkr_p0
	s_lshl_b32 s30, s29, 8
	v_add_u32_e32 v15, s30, v14
	ds_read_b128 v[48:51], v15
	ds_read_b128 v[52:55], v15 offset:16
.Lcv_nogkr_p0:
	s_lshl_b32 s30, s28, 6
	s_andn2_b32 s31, s30, 0x7f
	s_lshl_b32 s31, s31, 1
	s_and_b32 s23, s30, 64
	s_add_u32 s31, s31, s23
	s_add_u32 s31, s31, s10
	s_cmp_eq_u32 s9, 1
	s_cselect_b32 s31, s31, s30
	s_mul_i32 s31, s31, s7
	s_lshl_b32 s31, s31, 1
	s_lshl_b32 s23, s29, 7
	s_add_u32 s31, s31, s23
	s_add_u32 s20, s4, s31
	s_addc_u32 s21, s5, 0
	s_waitcnt lgkmcnt(0)
	s_cmp_eq_u32 s11, 0
	s_cbranch_scc1 .Lcv_nomul_p0
	v_pk_mul_f32 v[40:41], v[40:41], v[48:49]
	v_pk_mul_f32 v[42:43], v[42:43], v[50:51]
	v_pk_mul_f32 v[44:45], v[44:45], v[52:53]
	v_pk_mul_f32 v[46:47], v[46:47], v[54:55]
.Lcv_nomul_p0:
	v_cvt_pk_bf16_f32 v40, v40, v41
	v_cvt_pk_bf16_f32 v41, v42, v43
	v_cvt_pk_bf16_f32 v42, v44, v45
	v_cvt_pk_bf16_f32 v43, v46, v47
	s_cmp_lt_u32 s30, s27
	s_cselect_b32 s23, 1, 0
	s_bitcmp0_b32 s30, 6
	s_cselect_b32 s31, 1, 0
	s_and_b32 s23, s23, s31
	s_cbranch_scc1 .Lcv_perm_p0
	global_store_dwordx4 v11, v[40:43], s[20:21]
	s_branch .Lcv_std_p0
.Lcv_perm_p0:
	global_store_dwordx4 v12, v[40:43], s[20:21]
.Lcv_std_p0:
	v_xor_b32_e32 v4, 0x8000, v4
	v_xor_b32_e32 v5, 0x8000, v5
	v_xor_b32_e32 v6, 0x8000, v6
	v_xor_b32_e32 v9, 0x8000, v9
	v_xor_b32_e32 v10, 0x8000, v10
	s_add_u32 s14, s14, s16
.Lcv_st_p1:
	s_cmp_ge_u32 s14, s8
	s_cbranch_scc1 .Lcv_done
	s_add_u32 s22, s14, s17
	s_cmp_lt_u32 s22, s8
	s_cbranch_scc1 .Lcv_fast_p1
	s_waitcnt vmcnt(0)
	s_branch .Lcv_go_p1
.Lcv_fast_p1:
	s_waitcnt vmcnt(5)
.Lcv_go_p1:
	ds_write2_b32 v4, v24, v25 offset1:1
	ds_write2_b32 v4, v26, v27 offset0:2 offset1:3
	ds_write2_b32 v5, v28, v29 offset1:1
	ds_write2_b32 v6, v30, v31 offset1:1
	s_waitcnt lgkmcnt(0)
	s_barrier
	s_add_u32 s23, s22, s16
	s_cmp_ge_u32 s23, s8
	s_cbranch_scc1 .Lcv_nold_p1
	s_lshr_b32 s28, s23, 5
	s_mul_hi_u32 s29, s23, 0x2e8ba2e9
	s_lshr_b32 s29, s29, 4
	s_cmpk_eq_u32 s7, 0x1600
	s_cselect_b32 s28, s29, s28
	s_mul_i32 s29, s28, s25
	s_sub_u32 s29, s23, s29
	s_lshl_b32 s30, s6, 8
	s_mul_i32 s30, s29, s30
	s_lshl_b32 s31, s28, 8
	s_add_u32 s30, s30, s31
	s_add_u32 s18, s2, s30
	s_addc_u32 s19, s3, 0
	global_load_dwordx4 v[24:27], v2, s[18:19] nt
	global_load_dwordx4 v[28:31], v3, s[18:19] nt

; __device__ __forceinline__ void convert_w(LAS float* tile, const float* __restrict__ src, int K, int N, bf16_t* __restrict__ dst, int mode, int sidx, const float* __restrict__ gk, int G, int bid) {
;     ...
;         for (int i = 0; i < 2; ++i) {
;             const int k = kk + 32 * i;
;             tile[k * 65 + n4 + 0] = pv[i][0]; tile[k * 65 + n4 + 1] = pv[i][1]; tile[k * 65 + n4 + 2] = pv[i][2]; tile[k * 65 + n4 + 3] = pv[i][3];
;         }
;         __syncthreads();
;         if (t + G < ntile) {
;             const int k1 = ((t + G) % tk) * 64, n1 = ((t + G) / tk) * 64;
; #pragma unroll
;             for (int i = 0; i < 2; ++i) pv[i] = __builtin_nontemporal_load((const f32x4*)(src + (size_t)(k1 + kk + 32 * i) * N + n1 + n4));
;         }
.Lcv_go_p2:
	ds_write2_b32 v4, v32, v33 offset1:1
	ds_write2_b32 v4, v34, v35 offset0:2 offset1:3
	ds_write2_b32 v5, v36, v37 offset1:1
	ds_write2_b32 v6, v38, v39 offset1:1
	s_waitcnt lgkmcnt(0)
	s_barrier
	s_add_u32 s23, s22, s16
	s_cmp_ge_u32 s23, s8
	s_cbranch_scc1 .Lcv_nold_p2
	s_lshr_b32 s28, s23, 5
	s_mul_hi_u32 s29, s23, 0x2e8ba2e9
	s_lshr_b32 s29, s29, 4
	s_cmpk_eq_u32 s7, 0x1600
	s_cselect_b32 s28, s29, s28
	s_mul_i32 s29, s28, s25
	s_sub_u32 s29, s23, s29
	s_lshl_b32 s30, s6, 8
	s_mul_i32 s30, s29, s30
	s_lshl_b32 s31, s28, 8
	s_add_u32 s30, s30, s31
	s_add_u32 s18, s2, s30
	s_addc_u32 s19, s3, 0
	global_load_dwordx4 v[32:35], v2, s[18:19] nt
	global_load_dwordx4 v[36:39], v3, s[18:19] nt

; __device__ __forceinline__ void convert_w(LAS float* tile, const float* __restrict__ src, int K, int N, bf16_t* __restrict__ dst, int mode, int sidx, const float* __restrict__ gk, int G, int bid) {
;     ...
;         for (int i = 0; i < 2; ++i) {
;             const int k = kk + 32 * i;
;             tile[k * 65 + n4 + 0] = pv[i][0]; tile[k * 65 + n4 + 1] = pv[i][1]; tile[k * 65 + n4 + 2] = pv[i][2]; tile[k * 65 + n4 + 3] = pv[i][3];
;         }
;         __syncthreads();
.Lcv_fast_l0:
	s_waitcnt vmcnt(7)

; __device__ __forceinline__ unsigned cvt_pk_bf16(float lo, float hi) { unsigned r; asm volatile("v_cvt_pk_bf16_f32 %0, %1, %2" : "=v"(r) : "v"(lo), "v"(hi)); return r; }
; __device__ __forceinline__ void convert_w(LAS float* tile, const float* __restrict__ src, int K, int N, bf16_t* __restrict__ dst, int mode, int sidx, const float* __restrict__ gk, int G, int bid) {
;     ...
;     for (int t = bid; t < ntile; t += G) {
;         const int k0 = (t % tk) * 64, n0 = (t / tk) * 64;
; #pragma unroll
;         for (int i = 0; i < 2; ++i) {
;             const int k = kk + 32 * i;
;             tile[k * 65 + n4 + 0] = pv[i][0]; tile[k * 65 + n4 + 1] = pv[i][1]; tile[k * 65 + n4 + 2] = pv[i][2]; tile[k * 65 + n4 + 3] = pv[i][3];
;         }
;         __syncthreads();
;         if (t + G < ntile) {
;             const int k1 = ((t + G) % tk) * 64, n1 = ((t + G) / tk) * 64;
; #pragma unroll
;             for (int i = 0; i < 2; ++i) pv[i] = __builtin_nontemporal_load((const f32x4*)(src + (size_t)(k1 + kk + 32 * i) * N + n1 + n4));
;         }
;         const int n = tid >> 3, k8 = (tid & 7) * 8;
;         float f[8];
; #pragma unroll
;         for (int j = 0; j < 8; ++j) f[j] = tile[(k8 + j) * 65 + n];
;         if (gk) {
;             const f32x4 ga = *(const f32x4*)(gk + k0 + k8), gb = *(const f32x4*)(gk + k0 + k8 + 4);
;             f[0] *= ga[0]; f[1] *= ga[1]; f[2] *= ga[2]; f[3] *= ga[3]; f[4] *= gb[0]; f[5] *= gb[1]; f[6] *= gb[2]; f[7] *= gb[3];
;         }
;         u32x4 w; w.x = cvt_pk_bf16(f[0], f[1]); w.y = cvt_pk_bf16(f[2], f[3]); w.z = cvt_pk_bf16(f[4], f[5]); w.w = cvt_pk_bf16(f[6], f[7]);
;         const int nn = n0 + n;
;         int row = nn;
;         if (mode == 1) row = 256 * (nn >> 7) + 128 * sidx + (nn & 127);
;         if (mode == 2 && nn < 4096 && (nn & 127) < 32) { const int d = nn & 31; row = (nn & ~31) + 8 * ((d >> 2) & 3) + 4 * (d >> 4) + (d & 3); }
;         *(u32x4*)(dst + (size_t)row * K + k0 + k8) = w;
;         __syncthreads();
;     }
.Lcv_std_l2:
	v_xor_b32_e32 v4, 0x8000, v4
	v_xor_b32_e32 v5, 0x8000, v5
	v_xor_b32_e32 v6, 0x8000, v6
	v_xor_b32_e32 v9, 0x8000, v9
	v_xor_b32_e32 v10, 0x8000, v10
	s_add_u32 s14, s14, s16
	s_branch .Lcv_loop
.Lcv_done:
	s_waitcnt lgkmcnt(0)
	s_barrier
	v_readlane_b32 s0, v253, 0
	v_readlane_b32 s1, v253, 1
	v_readlane_b32 s2, v253, 2
	v_readlane_b32 s3, v253, 3
	v_readlane_b32 s4, v253, 4
	v_readlane_b32 s5, v253, 5
	v_readlane_b32 s6, v253, 6
	v_readlane_b32 s7, v253, 7
	v_readlane_b32 s8, v253, 8
	v_readlane_b32 s9, v253, 9
	v_readlane_b32 s10, v253, 10
	v_readlane_b32 s11, v253, 11
	v_readlane_b32 s12, v253, 12
	v_readlane_b32 s13, v253, 13
	v_readlane_b32 s14, v253, 14
	v_readlane_b32 s15, v253, 15
	v_readlane_b32 s16, v253, 16
	v_readlane_b32 s17, v253, 17
	v_readlane_b32 s18, v253, 18
	v_readlane_b32 s19, v253, 19
	v_readlane_b32 s20, v253, 20
	v_readlane_b32 s21, v253, 21
	v_readlane_b32 s22, v253, 22
	v_readlane_b32 s23, v253, 23
	v_readlane_b32 s24, v253, 24
	v_readlane_b32 s25, v253, 25
	v_readlane_b32 s26, v253, 26
	v_readlane_b32 s27, v253, 27
	v_readlane_b32 s28, v253, 28
	v_readlane_b32 s29, v253, 29
	v_readlane_b32 s30, v253, 30
	v_readlane_b32 s31, v253, 31
	s_nop 4
	s_cmp_eq_u32 s98, 0
	s_cbranch_scc1 .Lcv_ret_0
	s_cmp_eq_u32 s98, 1
	s_cbranch_scc1 .Lcv_ret_1
	s_cmp_eq_u32 s98, 2
	s_cbranch_scc1 .Lcv_ret_2
	s_cmp_eq_u32 s98, 3
	s_cbranch_scc1 .Lcv_ret_3
	s_cmp_eq_u32 s98, 4
	s_cbranch_scc1 .Lcv_ret_4
	s_cmp_eq_u32 s98, 5
	s_cbranch_scc1 .Lcv_ret_5
	s_cmp_eq_u32 s98, 6
	s_cbranch_scc1 .Lcv_ret_6
	s_cmp_eq_u32 s98, 7
	s_cbranch_scc1 .Lcv_ret_7
	s_cmp_eq_u32 s98, 8
	s_cbranch_scc1 .Lcv_ret_8
	s_cmp_eq_u32 s98, 9
	s_cbranch_scc1 .Lcv_ret_9
	s_cmp_eq_u32 s98, 10
	s_cbranch_scc1 .Lcv_ret_10
	s_cmp_eq_u32 s98, 11
	s_cbranch_scc1 .Lcv_ret_11
	s_cmp_eq_u32 s98, 12
	s_cbranch_scc1 .Lcv_ret_12
	s_cmp_eq_u32 s98, 13
	s_cbranch_scc1 .Lcv_ret_13
	s_cmp_eq_u32 s98, 14
	s_cbranch_scc1 .Lcv_ret_14
	s_cmp_eq_u32 s98, 15
	s_cbranch_scc1 .Lcv_ret_15
	s_branch .Lcv_ret_0

; #define LAS __attribute__((address_space(3)))
; #define PG8_WAIT_V(n) asm volatile("s_waitcnt vmcnt(" #n ")" ::: "memory")
; #define PG8_BAR __builtin_amdgcn_s_barrier()
; template <class Epi>
; __device__ __forceinline__ void gemm_phase(LAS unsigned char* lds, const Gemm g, const StaticOrder S, const Epi E) {
;     ...
;     PG8_WAIT_V(0);
;     PG8_BAR;
; __global__ void __launch_bounds__(NTHR, 2) mega_fwd(Params p) {
;     ...
;     if (IN(8)) {
;         convert_w((LAS float*)lds, p.w2 + (size_t)2 * WSZ, DFF, DM, W2, 0, 0, nullptr, G, bid);
;         convert_w((LAS float*)lds, p.w1 + (size_t)2 * WSZ, DM, DFF, W13, 1, 0, NG + 3 * DM, G, bid);
;         convert_w((LAS float*)lds, p.w3 + (size_t)2 * WSZ, DM, DFF, W13, 1, 1, NG + 3 * DM, G, bid);
.LBB0_779:
	s_waitcnt vmcnt(0)
	v_readlane_b32 s56, v252, 15
	v_readlane_b32 s57, v252, 16
	s_barrier
	s_mov_b32 s98, 8
	s_branch .Lcv_entry
.Lcv_ret_8:
	s_mov_b32 s98, 9
	s_branch .Lcv_entry
.Lcv_ret_9:
	s_mov_b32 s98, 10
	s_branch .Lcv_entry

; #define LAS __attribute__((address_space(3)))
; __device__ __forceinline__ void convert_w(LAS float* tile, const float* __restrict__ src, int K, int N, bf16_t* __restrict__ dst, int mode, int sidx, const float* __restrict__ gk, int G, int bid) {
;     ...
;     if (bid < ntile) {
;         const int k0 = (bid % tk) * 64, n0 = (bid / tk) * 64;
; #pragma unroll
;         for (int i = 0; i < 2; ++i) pv[i] = __builtin_nontemporal_load((const f32x4*)(src + (size_t)(k0 + kk + 32 * i) * N + n0 + n4));
; __global__ void __launch_bounds__(NTHR, 2) mega_fwd(Params p) {
;     ...
;     if (IN(11)) { Gemm g{BIG, W2, DFF, DFF, SEQ, DM, DFF, 0, 1}; StaticOrder S; S.init(SEQ, DM, G, bid, 4); EpiResid<true, 4> E{RS}; gemm_phase(lds, g, S, E); }
;     if (IN(11)) convert_w((LAS float*)lds, p.w_qkv, DM, 6144, WA, 2, 0, NG + 4 * DM, G, bid);
.LBB0_965:
	s_mov_b32 s98, 11
	s_branch .Lcv_entry
.Lcv_ret_11:
	s_cmpk_gt_i32 s79, -1
	s_cbranch_scc1 .LBB0_970
	v_readlane_b32 s0, v252, 0
	s_ashr_i32 s2, s79, 31
	v_readlane_b32 s1, v252, 1
	s_lshr_b32 s2, s2, 27
	s_load_dwordx2 s[0:1], s[0:1], 0x58
	s_add_i32 s2, s79, s2
	s_and_b32 s3, s2, 0x3ffe0
	s_lshl_b32 s2, s2, 1
	s_sub_i32 s3, s79, s3
	s_andn2_b32 s2, s2, 63
	v_lshl_or_b32 v2, s3, 6, v161
	s_ashr_i32 s3, s2, 31
	s_lshl_b64 s[2:3], s[2:3], 2
	v_and_b32_e32 v0, 60, v164
	s_waitcnt lgkmcnt(0)
	s_add_u32 s2, s0, s2
	s_addc_u32 s3, s1, s3
	v_lshlrev_b32_e32 v8, 2, v0
	v_mov_b32_e32 v9, 0
	v_mul_i32_i24_e32 v2, 0x1800, v2
	v_lshl_add_u64 v[0:1], s[2:3], 0, v[8:9]
	v_ashrrev_i32_e32 v3, 31, v2
	v_lshl_add_u64 v[10:11], v[2:3], 2, v[0:1]
	s_mov_b32 s2, 0xc0000
	v_add_co_u32_e32 v12, vcc, s2, v10
	v_add_u32_e32 v16, 0, v8
	s_nop 0
	v_addc_co_u32_e32 v13, vcc, 0, v11, vcc
	global_load_dwordx4 v[0:3], v[10:11], off nt
	global_load_dwordx4 v[4:7], v[12:13], off nt
	v_lshl_add_u64 v[10:11], s[0:1], 0, v[8:9]
	v_lshlrev_b32_e32 v8, 3, v224
	v_and_b32_e32 v20, 56, v8
	v_readlane_b32 s0, v252, 7
	v_lshlrev_b32_e32 v8, 2, v20
	v_readlane_b32 s1, v252, 8
	v_bfe_u32 v14, v224, 3, 2
	v_mul_u32_u24_e32 v17, 0x104, v161
	v_lshl_add_u64 v[12:13], s[0:1], 0, v[8:9]
	s_mov_b64 s[0:1], 0x8000
	v_lshl_add_u64 v[12:13], v[12:13], 0, s[0:1]
	s_add_i32 s0, s78, s79
	v_and_b32_e32 v8, 24, v163
	s_mul_i32 s0, s0, 0x60000
	s_movk_i32 s2, 0x1800
	v_lshl_add_u32 v19, v160, 2, 0
	v_mul_u32_u24_e32 v21, 0x104, v20
	v_or3_b32 v14, v8, v14, v162
	v_mov_b32_e32 v8, s0
	v_add_u32_e32 v16, v16, v17
	s_lshl_b32 s4, s79, 6
	s_lshl_b32 s5, s78, 6
	v_mad_u32_u24 v15, v161, s2, v8
	s_mul_i32 s8, s78, 0x60000
	v_add_u32_e32 v17, 0x2080, v16
	v_add_u32_e32 v18, 0x2088, v16
	v_add_u32_e32 v19, v19, v21
	s_movk_i32 s9, 0x1000
	s_movk_i32 s10, 0xff80
	v_lshlrev_b32_e32 v8, 1, v20
	s_mov_b32 s2, s79
	s_branch .LBB0_968

; #define LAS __attribute__((address_space(3)))
; __device__ __forceinline__ void convert_w(LAS float* tile, const float* __restrict__ src, int K, int N, bf16_t* __restrict__ dst, int mode, int sidx, const float* __restrict__ gk, int G, int bid) {
;     ...
;     if (bid < ntile) {
;         const int k0 = (bid % tk) * 64, n0 = (bid / tk) * 64;
; #pragma unroll
;         for (int i = 0; i < 2; ++i) pv[i] = __builtin_nontemporal_load((const f32x4*)(src + (size_t)(k0 + kk + 32 * i) * N + n0 + n4));
; __global__ void __launch_bounds__(NTHR, 2) mega_fwd(Params p) {
;     ...
;     if (IN(14)) combine_phase(OG, LSE, XN, G, bid);
;     if (IN(14)) convert_w((LAS float*)lds, p.w_o, DM, DM, WB, 0, 0, nullptr, G, bid);
.LBB0_1296:
	s_or_b64 exec, exec, s[0:1]
	s_mov_b32 s98, 12
	s_branch .Lcv_entry
.Lcv_ret_12:
	s_cmpk_gt_i32 s79, -1
	s_cbranch_scc1 .LBB0_1301
	v_readlane_b32 s0, v252, 0
	s_ashr_i32 s4, s79, 31
	v_readlane_b32 s1, v252, 1
	s_lshr_b32 s4, s4, 27
	s_load_dwordx2 s[0:1], s[0:1], 0x60
	s_add_i32 s4, s79, s4
	s_and_b32 s5, s4, 0x3ffffe0
	s_lshl_b32 s4, s4, 1
	v_lshrrev_b32_e32 v14, 4, v224
	s_sub_i32 s5, s79, s5
	s_andn2_b32 s4, s4, 63
	s_waitcnt vmcnt(2)
	v_lshl_or_b32 v0, s5, 6, v14
	s_ashr_i32 s5, s4, 31
	s_lshl_b64 s[4:5], s[4:5], 2
	s_waitcnt lgkmcnt(0)
	s_add_u32 s4, s0, s4
	v_lshlrev_b32_e32 v1, 4, v224
	s_addc_u32 s5, s1, s5
	v_and_b32_e32 v8, 0xf0, v1
	v_mov_b32_e32 v9, 0
	v_ashrrev_i32_e32 v1, 31, v0
	v_lshl_add_u64 v[2:3], s[4:5], 0, v[8:9]
	v_lshlrev_b64 v[0:1], 13, v[0:1]
	v_lshl_add_u64 v[10:11], v[2:3], 0, v[0:1]
	s_mov_b32 s4, 0x40000
	v_add_co_u32_e32 v12, vcc, s4, v10
	v_add_u32_e32 v15, 0, v8
	s_nop 0
	v_addc_co_u32_e32 v13, vcc, 0, v11, vcc
	global_load_dwordx4 v[0:3], v[10:11], off nt
	global_load_dwordx4 v[4:7], v[12:13], off nt
	v_lshl_add_u64 v[10:11], s[0:1], 0, v[8:9]
	v_lshlrev_b32_e32 v8, 3, v224
	v_lshrrev_b32_e32 v12, 3, v224
	v_and_b32_e32 v8, 56, v8
	v_lshl_add_u32 v17, v12, 2, 0
	v_mul_u32_u24_e32 v16, 0x104, v14
	v_mul_u32_u24_e32 v18, 0x104, v8
	s_lshl_b32 s5, s78, 6
	v_or_b32_e32 v13, s5, v14
	v_add_u32_e32 v14, v15, v16
	v_add_u32_e32 v17, v17, v18
	s_lshl_b32 s4, s79, 6
	v_add_u32_e32 v15, 0x2080, v14
	v_add_u32_e32 v16, 0x2088, v14
	v_lshlrev_b32_e32 v8, 1, v8
	v_add_u32_e32 v18, 0x400, v17
	s_mov_b32 s7, s79
	s_branch .LBB0_1299

; #define LAS __attribute__((address_space(3)))
; #define PG8_WAIT_V(n) asm volatile("s_waitcnt vmcnt(" #n ")" ::: "memory")
; #define PG8_BAR __builtin_amdgcn_s_barrier()
; template <class Epi>
; __device__ __forceinline__ void gemm_phase(LAS unsigned char* lds, const Gemm g, const StaticOrder S, const Epi E) {
;     ...
;     PG8_WAIT_V(0);
;     PG8_BAR;
; __global__ void __launch_bounds__(NTHR, 2) mega_fwd(Params p) {
;     ...
;     if (IN(15)) { Gemm g{XN, WB, DM, DM, SEQ, DM, DM, 0}; StaticOrder S; S.init(SEQ, DM, G, bid, 4); EpiResid<false, 5> E{RS}; gemm_phase(lds, g, S, E); }
;     if (IN(15)) {
;         convert_w((LAS float*)lds, p.w2 + (size_t)3 * WSZ, DFF, DM, W2 + (size_t)DM * DFF, 0, 0, nullptr, G, bid);
;         convert_w((LAS float*)lds, p.w1 + (size_t)3 * WSZ, DM, DFF, W13 + (size_t)2 * DFF * DM, 1, 0, NG + 5 * DM, G, bid);
;         convert_w((LAS float*)lds, p.w3 + (size_t)3 * WSZ, DM, DFF, W13 + (size_t)2 * DFF * DM, 1, 1, NG + 5 * DM, G, bid);
.LBB0_1399:
	s_waitcnt vmcnt(0)
	s_barrier
	s_mov_b32 s98, 13
	s_branch .Lcv_entry
.Lcv_ret_13:
	s_mov_b32 s98, 14
	s_branch .Lcv_entry
.Lcv_ret_14:
	s_mov_b32 s98, 15
	s_branch .Lcv_entry

; #define LAS __attribute__((address_space(3)))
; __global__ void __launch_bounds__(NTHR, 2) mega_fwd(Params p) {
;     extern __shared__ __attribute__((aligned(16))) unsigned char lds_raw[];
;     LAS unsigned char* lds = (LAS unsigned char*)lds_raw;
;     const int G = gridDim.x, bid = blockIdx.x;
	.amdhsa_kernel _Z8mega_fwd6Params
		.amdhsa_group_segment_fixed_size 0
		.amdhsa_private_segment_fixed_size 0
		.amdhsa_kernarg_size 456
		.amdhsa_user_sgpr_count 2
		.amdhsa_user_sgpr_dispatch_ptr 0
		.amdhsa_user_sgpr_queue_ptr 0
		.amdhsa_user_sgpr_kernarg_segment_ptr 1
		.amdhsa_user_sgpr_dispatch_id 0
		.amdhsa_user_sgpr_kernarg_preload_length 0
		.amdhsa_user_sgpr_kernarg_preload_offset 0
		.amdhsa_user_sgpr_private_segment_size 0
		.amdhsa_uses_dynamic_stack 0
		.amdhsa_enable_private_segment 0
		.amdhsa_system_sgpr_workgroup_id_x 1
		.amdhsa_system_sgpr_workgroup_id_y 0
		.amdhsa_system_sgpr_workgroup_id_z 0
		.amdhsa_system_sgpr_workgroup_info 0
		.amdhsa_system_vgpr_workitem_id 2
		.amdhsa_next_free_vgpr 254
		.amdhsa_next_free_sgpr 100
		.amdhsa_accum_offset 256
		.amdhsa_reserve_vcc 1
		.amdhsa_float_round_mode_32 0
		.amdhsa_float_round_mode_16_64 0
		.amdhsa_float_denorm_mode_32 3
		.amdhsa_float_denorm_mode_16_64 3
		.amdhsa_dx10_clamp 1
		.amdhsa_ieee_mode 1
		.amdhsa_fp16_overflow 0
		.amdhsa_tg_split 0
		.amdhsa_exception_fp_ieee_invalid_op 0
		.amdhsa_exception_fp_denorm_src 0
		.amdhsa_exception_fp_ieee_div_zero 0
		.amdhsa_exception_fp_ieee_overflow 0
		.amdhsa_exception_fp_ieee_underflow 0
		.amdhsa_exception_fp_ieee_inexact 0
		.amdhsa_exception_int_div_zero 0
	.end_amdhsa_kernel

; #define LAS __attribute__((address_space(3)))
; __global__ void __launch_bounds__(NTHR, 2) mega_fwd(Params p) {
;     extern __shared__ __attribute__((aligned(16))) unsigned char lds_raw[];
;     LAS unsigned char* lds = (LAS unsigned char*)lds_raw;
;     const int G = gridDim.x, bid = blockIdx.x;
amdhsa.kernels:
  - .agpr_count:     0
    .args:
      - .offset:         0
        .size:           200
        .value_kind:     by_value
      - .offset:         200
        .size:           4
        .value_kind:     hidden_block_count_x
      - .offset:         204
        .size:           4
        .value_kind:     hidden_block_count_y
      - .offset:         208
        .size:           4
        .value_kind:     hidden_block_count_z
      - .offset:         212
        .size:           2
        .value_kind:     hidden_group_size_x
      - .offset:         214
        .size:           2
        .value_kind:     hidden_group_size_y
      - .offset:         216
        .size:           2
        .value_kind:     hidden_group_size_z
      - .offset:         218
        .size:           2
        .value_kind:     hidden_remainder_x
      - .offset:         220
        .size:           2
        .value_kind:     hidden_remainder_y
      - .offset:         222
        .size:           2
        .value_kind:     hidden_remainder_z
      - .offset:         240
        .size:           8
        .value_kind:     hidden_global_offset_x
      - .offset:         248
        .size:           8
        .value_kind:     hidden_global_offset_y
      - .offset:         256
        .size:           8
        .value_kind:     hidden_global_offset_z
      - .offset:         264
        .size:           2
        .value_kind:     hidden_grid_dims
      - .offset:         288
        .size:           8
        .value_kind:     hidden_multigrid_sync_arg
      - .offset:         320
        .size:           4
        .value_kind:     hidden_dynamic_lds_size
    .group_segment_fixed_size: 0
    .kernarg_segment_align: 8
    .kernarg_segment_size: 456
    .language:       OpenCL C
    .language_version:
      - 2
      - 0
    .max_flat_workgroup_size: 512
    .name:           _Z8mega_fwd6Params
    .private_segment_fixed_size: 0
    .sgpr_count:     106
    .sgpr_spill_count: 148
    .symbol:         _Z8mega_fwd6Params.kd
    .uniform_work_group_size: 1
    .uses_dynamic_stack: false
    .vgpr_count:     254
    .vgpr_spill_count: 0
    .wavefront_size: 64
